# v98 plus the same odd-XCD 1.4 us start stagger at the GEMM1 phase
# speedup vs baseline: 1.0041x; 1.0041x over previous
; #define LAS __attribute__((address_space(3)))
; DI TJob small_job(const Params& p, int j) {
;     TJob r; constexpr int J_SQ = 32 * 32;
;     if (j < 3 * J_SQ) { const int which = j >> 10, q = j & 1023, nt = q >> 5, kt = q & 31;
;         r.src = p.in[11 + which]; r.dst = (bf16_t*)(p.ws + (which == 0 ? WS_WAT : which == 1 ? WS_WBT : WS_WOT)); r.ld_src = DM; r.ld_dst = DM; r.k0 = kt * 64; r.n0 = nt * 64; }
;     else { const int jj = j - 3 * J_SQ, gate = jj >> 7, q = jj & 127, blk = q >> 2, sub = q & 3, d = blk >> 4, nb = blk & 15;
;         r.src = p.in[gate == 0 ? 5 : 7] + (size_t)blk * 16384; r.dst = (bf16_t*)(p.ws + WS_LWT) + (size_t)((d * 2 + gate) * 16 + nb) * 16384;
;         r.ld_src = 128; r.ld_dst = 128; r.k0 = (sub >> 1) * 64; r.n0 = (sub & 1) * 64; }
; __global__ void __launch_bounds__(512, 2) mega(Params p) {
;     ...
;     if (PH(1)) {
;         pg8::Gemm g; g.A0 = (const bf16_t*)((unsigned char*)p.out + DO_XN); g.A1 = g.A0; g.B0 = (const bf16_t*)((unsigned char*)p.out + DO_WINT); g.B1 = g.B0;
;         g.lda = DM; g.ldb = DM; g.M = S; g.N = NIN; g.K = DM; g.ksplit = DM / 64;
;         pg8::StaticOrder so; so.init(g.M, g.N, (int)gridDim.x, (int)blockIdx.x);
;         EpiZ e; e.ws = p.ws;
;         const bool two_cls = (gridDim.x >= 16 && (gridDim.x & 15) == 0);
;         const int fcls = (blockIdx.x >> 3) & 1, fidx = (int)((blockIdx.x >> 4) * 8 + (blockIdx.x & 7)), fhalf = (int)(gridDim.x / 2);
;         if (two_cls) { if (fcls) prep_small_weights(p, shm, fidx, fhalf, 1664); }
;         else prep_small_weights(p, shm, (int)blockIdx.x, (int)gridDim.x);
;         pg8::gemm_phase<EpiZ>((LAS unsigned char*)shm, g, so, e);
;         if (two_cls && !fcls) prep_small_weights(p, shm, 1664 + fidx, fhalf);
.LBB0_80:
	s_waitcnt lgkmcnt(0)
	s_cmp_lt_i32 s4, 2
	s_cselect_b64 s[6:7], -1, 0
	s_cmp_gt_i32 s5, 1
	s_cselect_b64 s[4:5], -1, 0
	s_and_b64 s[4:5], s[6:7], s[4:5]
	s_andn2_b64 vcc, exec, s[4:5]
	s_cbranch_vccnz .LBB0_157
	s_bitcmp1_b32 s2, 0
	s_cbranch_scc0 .Lp1_nostag
	s_sleep 38
.Lp1_nostag:
	s_cmp_gt_u32 s24, 15
	s_load_dwordx4 s[8:11], s[0:1], 0x78
	s_cselect_b64 s[4:5], -1, 0
	s_and_b32 s6, s24, 15
	s_cmp_eq_u32 s6, 0
	s_cselect_b64 s[6:7], -1, 0
	s_and_b64 s[12:13], s[4:5], s[6:7]
	s_lshr_b32 s4, s2, 1
	s_and_b32 s30, s4, 0x7ffffff8
	s_and_b32 s31, s2, 7
	s_andn2_b64 vcc, exec, s[12:13]
	s_mov_b64 s[4:5], -1
	s_cbranch_vccz .LBB0_97
	s_cmpk_gt_i32 s2, 0xcff
	s_cbranch_scc1 .LBB0_96
	s_cmpk_gt_i32 s2, 0xbff
	s_cbranch_scc0 .LBB0_85
	s_add_i32 s4, s2, 0xfffff400
	s_lshr_b32 s6, s4, 7
	s_bfe_u32 s14, s2, 0x40002
	s_cmpk_lt_u32 s4, 0x80
	s_cselect_b32 s4, 40, 56
	s_add_u32 s4, s0, s4
	s_addc_u32 s5, s1, 0
	s_load_dwordx2 s[4:5], s[4:5], 0x0
	s_lshl_b32 s15, s2, 14
	s_and_b32 s15, s15, 0x1f0000
	s_mov_b32 s7, 0
	s_waitcnt lgkmcnt(0)
	s_add_u32 s16, s4, s15
	s_addc_u32 s17, s5, 0
	s_lshr_b32 s4, s2, 5
	s_and_b32 s4, s4, 2
	s_add_i32 s4, s4, s6
	s_lshl_b32 s4, s4, 4
	s_or_b32 s6, s4, s14
	s_lshl_b64 s[4:5], s[6:7], 15
	s_add_u32 s4, s10, s4
	s_addc_u32 s5, s11, s5
	s_add_u32 s4, s4, 0x1c000000
	s_addc_u32 s5, s5, 0
	s_mov_b64 s[6:7], 0
	s_branch .LBB0_86
